# cross-attention phase rewritten by hand (all four kv tiles staged up front, same tile machinery as the differential attention)
# baseline (speedup 1.0000x reference)
.LBB0_135:
	s_and_b64 vcc, exec, s[0:1]
	s_cbranch_vccz .LBB0_159
	v_readlane_b32 s0, v255, 12
	s_cmpk_gt_i32 s0, 0x1ff
	s_cbranch_scc1 .LBB0_159
	s_mov_b32 s24, m0
	v_readfirstlane_b32 s4, v198
	v_readlane_b32 s38, v255, 12
	v_readlane_b32 s18, v255, 16
	s_lshr_b32 s27, s4, 6
	s_lshl_b32 s16, s27, 10
	v_and_b32_e32 v228, 31, v246
	v_lshrrev_b32_e32 v229, 5, v246
	v_lshlrev_b32_e32 v200, 9, v246
	s_lshl_b32 s4, s27, 4
	v_add_u32_e32 v200, s4, v200
	v_lshrrev_b32_e32 v230, 2, v246
	s_and_b32 s4, s27, 3
	s_lshl_b32 s4, s4, 4
	v_add_u32_e32 v230, s4, v230
	v_lshlrev_b32_e32 v230, 9, v230
	v_and_b32_e32 v231, 3, v246
	v_lshlrev_b32_e32 v231, 4, v231
	s_lshr_b32 s4, s27, 2
	s_lshl_b32 s4, s4, 6
	v_add3_u32 v201, v230, v231, s4
	s_lshl_b32 s4, s27, 5
	v_add_u32_e32 v230, s4, v228
	v_lshlrev_b32_e32 v225, 9, v230
	v_lshl_add_u32 v225, v229, 4, v225
	v_lshlrev_b32_e32 v203, 10, v229
	v_lshl_add_u32 v203, v228, 4, v203
	v_bfe_u32 v230, v246, 4, 1
	v_lshlrev_b32_e32 v230, 5, v230
	v_and_b32_e32 v231, 3, v246
	v_lshl_add_u32 v230, v231, 3, v230
	v_bfe_u32 v231, v246, 2, 2
	v_lshl_add_u32 v231, v229, 2, v231
	v_lshl_add_u32 v230, v231, 6, v230
	v_add_u32_e32 v204, 0x8000, v230
	s_lshl_b32 s4, s27, 8
	s_add_i32 s4, s4, 0x10000
	v_lshl_add_u32 v220, v228, 2, s4
	v_lshl_add_u32 v221, v229, 4, s4
	s_lshl_b32 s4, s27, 11
	s_add_i32 s4, s4, 0x10800
	v_lshlrev_b32_e32 v230, 8, v229
	v_lshl_add_u32 v230, v228, 1, v230
	v_add_u32_e32 v222, s4, v230
	v_lshrrev_b32_e32 v230, 2, v246
	v_and_b32_e32 v231, 3, v246
	v_lshlrev_b32_e32 v223, 6, v230
	v_lshl_add_u32 v223, v231, 4, v223
	v_add_u32_e32 v223, s4, v223
	s_lshl_b32 s4, s27, 5
	v_add_u32_e32 v230, s4, v230
	v_lshlrev_b32_e32 v224, 9, v230
	v_lshl_add_u32 v224, v231, 4, v224
	s_mov_b32 s26, 0
.Lxa_unit:
	s_lshl_b32 s19, s38, 1
	s_add_i32 s19, s19, s26
	s_lshr_b32 s5, s19, 6
	s_bfe_u32 s7, s19, 0x20004
	s_and_b32 s6, s19, 15
	s_lshl_b32 s14, s5, 12
	s_lshl_b32 s6, s6, 8
	s_add_i32 s6, s6, s14
	s_lshl_b32 s7, s7, 7
	s_lshl_b32 s14, s6, 9
	s_add_i32 s14, s14, s7
	s_add_u32 s74, s54, s14
	s_addc_u32 s75, s55, 0
	s_add_i32 s15, s14, 0x9600000
	s_add_u32 s76, s48, s15
	s_addc_u32 s77, s49, 0
	s_lshl_b32 s14, s5, 17
	s_add_i32 s14, s14, s7
	s_lshl_b32 s15, s18, 20
	s_add_i32 s14, s14, s15
	s_add_i32 s15, s14, 0x800000
	s_add_u32 s78, s48, s15
	s_addc_u32 s79, s49, 0
	s_add_i32 s15, s14, 0xc00000
	s_add_u32 s20, s48, s15
	s_addc_u32 s21, s49, 0
	global_load_dwordx4 v[148:151], v225, s[74:75] offset:0
	global_load_dwordx4 v[152:155], v225, s[74:75] offset:32
	global_load_dwordx4 v[156:159], v225, s[74:75] offset:64
	global_load_dwordx4 v[160:163], v225, s[74:75] offset:96
	s_add_i32 s4, s16, 0x0
	s_mov_b32 m0, s4
	s_add_i32 s5, s16, 0x8000
	global_load_lds_dwordx4 v200, s[78:79]
	s_mov_b32 m0, s5
	s_add_u32 s78, s78, 0x8000
	global_load_lds_dwordx4 v201, s[20:21]
	s_addc_u32 s79, s79, 0
	s_add_u32 s20, s20, 0x8000
	s_addc_u32 s21, s21, 0
	s_add_i32 s4, s16, 0x2000
	s_mov_b32 m0, s4
	s_add_i32 s5, s16, 0xa000
	global_load_lds_dwordx4 v200, s[78:79]
	s_mov_b32 m0, s5
	s_add_u32 s78, s78, 0x8000
	global_load_lds_dwordx4 v201, s[20:21]
	s_addc_u32 s79, s79, 0
	s_add_u32 s20, s20, 0x8000
	s_addc_u32 s21, s21, 0
	s_add_i32 s4, s16, 0x4000
	s_mov_b32 m0, s4
	s_add_i32 s5, s16, 0xc000
	global_load_lds_dwordx4 v200, s[78:79]
	s_mov_b32 m0, s5
	s_add_u32 s78, s78, 0x8000
	global_load_lds_dwordx4 v201, s[20:21]
	s_addc_u32 s79, s79, 0
	s_add_u32 s20, s20, 0x8000
	s_addc_u32 s21, s21, 0
	v_mov_b32_e32 v0, 0
	v_mov_b32_e32 v1, 0
	v_mov_b32_e32 v2, 0
	v_mov_b32_e32 v3, 0
	v_mov_b32_e32 v4, 0
	v_mov_b32_e32 v5, 0
	v_mov_b32_e32 v6, 0
	v_mov_b32_e32 v7, 0
	v_mov_b32_e32 v8, 0
	v_mov_b32_e32 v9, 0
	v_mov_b32_e32 v10, 0
	v_mov_b32_e32 v11, 0
	v_mov_b32_e32 v12, 0
	v_mov_b32_e32 v13, 0
	v_mov_b32_e32 v14, 0
	v_mov_b32_e32 v15, 0
	v_mov_b32_e32 v16, 0
	v_mov_b32_e32 v17, 0
	v_mov_b32_e32 v18, 0
	v_mov_b32_e32 v19, 0
	v_mov_b32_e32 v20, 0
	v_mov_b32_e32 v21, 0
	v_mov_b32_e32 v22, 0
	v_mov_b32_e32 v23, 0
	v_mov_b32_e32 v24, 0
	v_mov_b32_e32 v25, 0
	v_mov_b32_e32 v26, 0
	v_mov_b32_e32 v27, 0
	v_mov_b32_e32 v28, 0
	v_mov_b32_e32 v29, 0
	v_mov_b32_e32 v30, 0
	v_mov_b32_e32 v31, 0
	v_mov_b32_e32 v100, 0
	v_mov_b32_e32 v101, 0
	v_mov_b32_e32 v102, 0
	v_mov_b32_e32 v103, 0
	v_mov_b32_e32 v104, 0
	v_mov_b32_e32 v105, 0
	v_mov_b32_e32 v106, 0
	v_mov_b32_e32 v107, 0
	v_mov_b32_e32 v108, 0
	v_mov_b32_e32 v109, 0
	v_mov_b32_e32 v110, 0
	v_mov_b32_e32 v111, 0
	v_mov_b32_e32 v112, 0
	v_mov_b32_e32 v113, 0
	v_mov_b32_e32 v114, 0
	v_mov_b32_e32 v115, 0
	v_mov_b32_e32 v210, 0
	v_mov_b32_e32 v232, 0
	v_mov_b32_e32 v233, 0
	v_mov_b32_e32 v234, 0
	v_mov_b32_e32 v235, 0
	s_mov_b32 s39, 0xf149f2ca
	s_mov_b32 s25, 0xf149f2ca
	s_waitcnt vmcnt(4)
	s_barrier
	v_mov_b32_e32 v205, v203
	ds_read_b128 v[116:119], v205 offset:0
	ds_read_b128 v[120:123], v205 offset:512
	ds_read_b128 v[124:127], v205 offset:2048
	ds_read_b128 v[128:131], v205 offset:2560
	ds_read_b128 v[132:135], v205 offset:4096
	ds_read_b128 v[136:139], v205 offset:4608
	ds_read_b128 v[140:143], v205 offset:6144
	ds_read_b128 v[144:147], v205 offset:6656
	s_add_i32 s4, s16, 0x6000
	s_mov_b32 m0, s4
	s_add_i32 s5, s16, 0xe000
	global_load_lds_dwordx4 v200, s[78:79]
	s_mov_b32 m0, s5
	s_add_u32 s78, s78, 0x8000
	global_load_lds_dwordx4 v201, s[20:21]
	s_addc_u32 s79, s79, 0
	s_add_u32 s20, s20, 0x8000
	s_addc_u32 s21, s21, 0
	v_mov_b32_e32 v206, v204
	s_waitcnt lgkmcnt(6)
	v_mfma_f32_32x32x16_bf16 v[64:79], v[116:119], v[148:151], v[100:115]
	v_mfma_f32_32x32x16_bf16 v[80:95], v[120:123], v[148:151], v[100:115]
	s_waitcnt lgkmcnt(4)
	v_mfma_f32_32x32x16_bf16 v[64:79], v[124:127], v[152:155], v[64:79]
	v_mfma_f32_32x32x16_bf16 v[80:95], v[128:131], v[152:155], v[80:95]
	s_waitcnt lgkmcnt(2)
	v_mfma_f32_32x32x16_bf16 v[64:79], v[132:135], v[156:159], v[64:79]
	v_mfma_f32_32x32x16_bf16 v[80:95], v[136:139], v[156:159], v[80:95]
	s_waitcnt lgkmcnt(0)
	v_mfma_f32_32x32x16_bf16 v[64:79], v[140:143], v[160:163], v[64:79]
	v_mfma_f32_32x32x16_bf16 v[80:95], v[144:147], v[160:163], v[80:95]
	ds_read_b64_tr_b16 v[164:165], v206 offset:0
	ds_read_b64_tr_b16 v[166:167], v206 offset:512
	ds_read_b64_tr_b16 v[168:169], v206 offset:4096
	ds_read_b64_tr_b16 v[170:171], v206 offset:4608
	ds_read_b64_tr_b16 v[172:173], v206 offset:1024
	ds_read_b64_tr_b16 v[174:175], v206 offset:1536
	ds_read_b64_tr_b16 v[176:177], v206 offset:5120
	ds_read_b64_tr_b16 v[178:179], v206 offset:5632
	ds_read_b64_tr_b16 v[180:181], v206 offset:2048
	ds_read_b64_tr_b16 v[182:183], v206 offset:2560
	ds_read_b64_tr_b16 v[184:185], v206 offset:6144
	ds_read_b64_tr_b16 v[186:187], v206 offset:6656
	ds_read_b64_tr_b16 v[188:189], v206 offset:3072
	ds_read_b64_tr_b16 v[190:191], v206 offset:3584
	ds_read_b64_tr_b16 v[192:193], v206 offset:7168
	ds_read_b64_tr_b16 v[194:195], v206 offset:7680
	s_nop 0
	s_nop 0
	v_max3_f32 v215, v64, v65, v80
	v_max3_f32 v216, v66, v67, v81
	v_max3_f32 v215, v215, v82, v83
	v_max3_f32 v216, v216, v68, v69
	v_max3_f32 v215, v215, v70, v71
	v_max3_f32 v216, v216, v84, v85
	v_max3_f32 v215, v215, v86, v87
	v_max3_f32 v216, v216, v72, v73
	v_max3_f32 v215, v215, v74, v75
	v_max3_f32 v216, v216, v88, v89
	v_max3_f32 v215, v215, v90, v91
	v_max3_f32 v216, v216, v76, v77
	v_max3_f32 v215, v215, v78, v79
	v_max3_f32 v216, v216, v92, v93
	v_max3_f32 v215, v215, v94, v95
	v_max_f32_e32 v214, v215, v216
	v_mov_b32_e32 v215, v214
	s_nop 1
	v_permlane32_swap_b32_e32 v214, v215
	s_nop 0
	v_max_f32_e32 v214, v214, v215
	v_cmp_lt_f32_e32 vcc, s39, v214
	s_cmp_lg_u64 vcc, 0
	s_cbranch_scc1 .Lxa_resc_1
.Lxa_back_2:
	v_exp_f32_e32 v64, v64
	v_exp_f32_e32 v65, v65
	v_exp_f32_e32 v66, v66
	v_exp_f32_e32 v67, v67
	v_exp_f32_e32 v68, v68
	v_exp_f32_e32 v69, v69
	v_exp_f32_e32 v70, v70
	v_exp_f32_e32 v71, v71
	s_nop 0
	v_add_f32_e32 v232, v232, v64
	v_add_f32_e32 v233, v233, v65
	v_add_f32_e32 v234, v234, v66
	v_add_f32_e32 v235, v235, v67
	v_add_f32_e32 v232, v232, v68
	v_add_f32_e32 v233, v233, v69
	v_add_f32_e32 v234, v234, v70
	v_add_f32_e32 v235, v235, v71
	v_cvt_pk_bf16_f32 v64, v64, v65
	v_cvt_pk_bf16_f32 v65, v66, v67
	v_cvt_pk_bf16_f32 v66, v68, v69
	v_cvt_pk_bf16_f32 v67, v70, v71
	s_waitcnt lgkmcnt(0)
	s_nop 0
	v_mfma_f32_32x32x16_bf16 v[0:15], v[64:67], v[164:167], v[0:15]
	v_exp_f32_e32 v72, v72
	v_exp_f32_e32 v73, v73
	v_exp_f32_e32 v74, v74
	v_exp_f32_e32 v75, v75
	v_mfma_f32_32x32x16_bf16 v[16:31], v[64:67], v[168:171], v[16:31]
	v_exp_f32_e32 v76, v76
	v_exp_f32_e32 v77, v77
	v_exp_f32_e32 v78, v78
	v_exp_f32_e32 v79, v79
	v_add_f32_e32 v232, v232, v72
	v_add_f32_e32 v233, v233, v73
	v_add_f32_e32 v234, v234, v74
	v_add_f32_e32 v235, v235, v75
	s_nop 0
	v_add_f32_e32 v232, v232, v76
	v_add_f32_e32 v233, v233, v77
	v_add_f32_e32 v234, v234, v78
	v_add_f32_e32 v235, v235, v79
	v_cvt_pk_bf16_f32 v72, v72, v73
	v_cvt_pk_bf16_f32 v73, v74, v75
	v_cvt_pk_bf16_f32 v74, v76, v77
	v_cvt_pk_bf16_f32 v75, v78, v79
	s_nop 1
	v_mfma_f32_32x32x16_bf16 v[0:15], v[72:75], v[172:175], v[0:15]
	v_exp_f32_e32 v80, v80
	v_exp_f32_e32 v81, v81
	v_exp_f32_e32 v82, v82
	v_exp_f32_e32 v83, v83
	v_mfma_f32_32x32x16_bf16 v[16:31], v[72:75], v[176:179], v[16:31]
	v_exp_f32_e32 v84, v84
	v_exp_f32_e32 v85, v85
	v_exp_f32_e32 v86, v86
	v_exp_f32_e32 v87, v87
	v_add_f32_e32 v232, v232, v80
	v_add_f32_e32 v233, v233, v81
	v_add_f32_e32 v234, v234, v82
	v_add_f32_e32 v235, v235, v83
	s_nop 0
	v_add_f32_e32 v232, v232, v84
	v_add_f32_e32 v233, v233, v85
	v_add_f32_e32 v234, v234, v86
	v_add_f32_e32 v235, v235, v87
	v_cvt_pk_bf16_f32 v80, v80, v81
	v_cvt_pk_bf16_f32 v81, v82, v83
	v_cvt_pk_bf16_f32 v82, v84, v85
	v_cvt_pk_bf16_f32 v83, v86, v87
	s_nop 1
	v_mfma_f32_32x32x16_bf16 v[0:15], v[80:83], v[180:183], v[0:15]
	v_exp_f32_e32 v88, v88
	v_exp_f32_e32 v89, v89
	v_exp_f32_e32 v90, v90
	v_exp_f32_e32 v91, v91
	v_mfma_f32_32x32x16_bf16 v[16:31], v[80:83], v[184:187], v[16:31]
	v_exp_f32_e32 v92, v92
	v_exp_f32_e32 v93, v93
	v_exp_f32_e32 v94, v94
	v_exp_f32_e32 v95, v95
	v_add_f32_e32 v232, v232, v88
	v_add_f32_e32 v233, v233, v89
	v_add_f32_e32 v234, v234, v90
	v_add_f32_e32 v235, v235, v91
	s_nop 0
	v_add_f32_e32 v232, v232, v92
	v_add_f32_e32 v233, v233, v93
	v_add_f32_e32 v234, v234, v94
	v_add_f32_e32 v235, v235, v95
	v_cvt_pk_bf16_f32 v88, v88, v89
	v_cvt_pk_bf16_f32 v89, v90, v91
	v_cvt_pk_bf16_f32 v90, v92, v93
	v_cvt_pk_bf16_f32 v91, v94, v95
	s_nop 1
	v_mfma_f32_32x32x16_bf16 v[0:15], v[88:91], v[188:191], v[0:15]
	v_mfma_f32_32x32x16_bf16 v[16:31], v[88:91], v[192:195], v[16:31]
	s_waitcnt vmcnt(4)
	s_waitcnt lgkmcnt(0)
	s_barrier
	s_mov_b32 s39, 0x41000000
	s_mov_b32 s25, 0
	v_add_u32_e32 v205, 0x2000, v203
	ds_read_b128 v[116:119], v205 offset:0
	ds_read_b128 v[120:123], v205 offset:512
	ds_read_b128 v[124:127], v205 offset:2048
	ds_read_b128 v[128:131], v205 offset:2560
	ds_read_b128 v[132:135], v205 offset:4096
	ds_read_b128 v[136:139], v205 offset:4608
	ds_read_b128 v[140:143], v205 offset:6144
	ds_read_b128 v[144:147], v205 offset:6656
	v_add_u32_e32 v206, 0x2000, v204
	s_waitcnt lgkmcnt(6)
	v_mfma_f32_32x32x16_bf16 v[64:79], v[116:119], v[148:151], v[100:115]
	v_mfma_f32_32x32x16_bf16 v[80:95], v[120:123], v[148:151], v[100:115]
	s_waitcnt lgkmcnt(4)
	v_mfma_f32_32x32x16_bf16 v[64:79], v[124:127], v[152:155], v[64:79]
	v_mfma_f32_32x32x16_bf16 v[80:95], v[128:131], v[152:155], v[80:95]
	s_waitcnt lgkmcnt(2)
	v_mfma_f32_32x32x16_bf16 v[64:79], v[132:135], v[156:159], v[64:79]
	v_mfma_f32_32x32x16_bf16 v[80:95], v[136:139], v[156:159], v[80:95]
	s_waitcnt lgkmcnt(0)
	v_mfma_f32_32x32x16_bf16 v[64:79], v[140:143], v[160:163], v[64:79]
	v_mfma_f32_32x32x16_bf16 v[80:95], v[144:147], v[160:163], v[80:95]
	ds_read_b64_tr_b16 v[164:165], v206 offset:0
	ds_read_b64_tr_b16 v[166:167], v206 offset:512
	ds_read_b64_tr_b16 v[168:169], v206 offset:4096
	ds_read_b64_tr_b16 v[170:171], v206 offset:4608
	ds_read_b64_tr_b16 v[172:173], v206 offset:1024
	ds_read_b64_tr_b16 v[174:175], v206 offset:1536
	ds_read_b64_tr_b16 v[176:177], v206 offset:5120
	ds_read_b64_tr_b16 v[178:179], v206 offset:5632
	ds_read_b64_tr_b16 v[180:181], v206 offset:2048
	ds_read_b64_tr_b16 v[182:183], v206 offset:2560
	ds_read_b64_tr_b16 v[184:185], v206 offset:6144
	ds_read_b64_tr_b16 v[186:187], v206 offset:6656
	ds_read_b64_tr_b16 v[188:189], v206 offset:3072
	ds_read_b64_tr_b16 v[190:191], v206 offset:3584
	ds_read_b64_tr_b16 v[192:193], v206 offset:7168
	ds_read_b64_tr_b16 v[194:195], v206 offset:7680
	s_nop 0
	s_nop 0
	v_max3_f32 v215, v64, v65, v80
	v_max3_f32 v216, v66, v67, v81
	v_max3_f32 v215, v215, v82, v83
	v_max3_f32 v216, v216, v68, v69
	v_max3_f32 v215, v215, v70, v71
	v_max3_f32 v216, v216, v84, v85
	v_max3_f32 v215, v215, v86, v87
	v_max3_f32 v216, v216, v72, v73
	v_max3_f32 v215, v215, v74, v75
	v_max3_f32 v216, v216, v88, v89
	v_max3_f32 v215, v215, v90, v91
	v_max3_f32 v216, v216, v76, v77
	v_max3_f32 v215, v215, v78, v79
	v_max3_f32 v216, v216, v92, v93
	v_max3_f32 v215, v215, v94, v95
	v_max_f32_e32 v214, v215, v216
	v_mov_b32_e32 v215, v214
	s_nop 1
	v_permlane32_swap_b32_e32 v214, v215
	s_nop 0
	v_max_f32_e32 v214, v214, v215
	v_cmp_lt_f32_e32 vcc, s39, v214
	s_cmp_lg_u64 vcc, 0
	s_cbranch_scc1 .Lxa_resc_3
.Lxa_back_4:
	v_exp_f32_e32 v64, v64
	v_exp_f32_e32 v65, v65
	v_exp_f32_e32 v66, v66
	v_exp_f32_e32 v67, v67
	v_exp_f32_e32 v68, v68
	v_exp_f32_e32 v69, v69
	v_exp_f32_e32 v70, v70
	v_exp_f32_e32 v71, v71
	s_nop 0
	v_add_f32_e32 v232, v232, v64
	v_add_f32_e32 v233, v233, v65
	v_add_f32_e32 v234, v234, v66
	v_add_f32_e32 v235, v235, v67
	v_add_f32_e32 v232, v232, v68
	v_add_f32_e32 v233, v233, v69
	v_add_f32_e32 v234, v234, v70
	v_add_f32_e32 v235, v235, v71
	v_cvt_pk_bf16_f32 v64, v64, v65
	v_cvt_pk_bf16_f32 v65, v66, v67
	v_cvt_pk_bf16_f32 v66, v68, v69
	v_cvt_pk_bf16_f32 v67, v70, v71
	s_waitcnt lgkmcnt(0)
	s_nop 0
	v_mfma_f32_32x32x16_bf16 v[0:15], v[64:67], v[164:167], v[0:15]
	v_exp_f32_e32 v72, v72
	v_exp_f32_e32 v73, v73
	v_exp_f32_e32 v74, v74
	v_exp_f32_e32 v75, v75
	v_mfma_f32_32x32x16_bf16 v[16:31], v[64:67], v[168:171], v[16:31]
	v_exp_f32_e32 v76, v76
	v_exp_f32_e32 v77, v77
	v_exp_f32_e32 v78, v78
	v_exp_f32_e32 v79, v79
	v_add_f32_e32 v232, v232, v72
	v_add_f32_e32 v233, v233, v73
	v_add_f32_e32 v234, v234, v74
	v_add_f32_e32 v235, v235, v75
	s_nop 0
	v_add_f32_e32 v232, v232, v76
	v_add_f32_e32 v233, v233, v77
	v_add_f32_e32 v234, v234, v78
	v_add_f32_e32 v235, v235, v79
	v_cvt_pk_bf16_f32 v72, v72, v73
	v_cvt_pk_bf16_f32 v73, v74, v75
	v_cvt_pk_bf16_f32 v74, v76, v77
	v_cvt_pk_bf16_f32 v75, v78, v79
	s_nop 1
	v_mfma_f32_32x32x16_bf16 v[0:15], v[72:75], v[172:175], v[0:15]
	v_exp_f32_e32 v80, v80
	v_exp_f32_e32 v81, v81
	v_exp_f32_e32 v82, v82
	v_exp_f32_e32 v83, v83
	v_mfma_f32_32x32x16_bf16 v[16:31], v[72:75], v[176:179], v[16:31]
	v_exp_f32_e32 v84, v84
	v_exp_f32_e32 v85, v85
	v_exp_f32_e32 v86, v86
	v_exp_f32_e32 v87, v87
	v_add_f32_e32 v232, v232, v80
	v_add_f32_e32 v233, v233, v81
	v_add_f32_e32 v234, v234, v82
	v_add_f32_e32 v235, v235, v83
	s_nop 0
	v_add_f32_e32 v232, v232, v84
	v_add_f32_e32 v233, v233, v85
	v_add_f32_e32 v234, v234, v86
	v_add_f32_e32 v235, v235, v87
	v_cvt_pk_bf16_f32 v80, v80, v81
	v_cvt_pk_bf16_f32 v81, v82, v83
	v_cvt_pk_bf16_f32 v82, v84, v85
	v_cvt_pk_bf16_f32 v83, v86, v87
	s_nop 1
	v_mfma_f32_32x32x16_bf16 v[0:15], v[80:83], v[180:183], v[0:15]
	v_exp_f32_e32 v88, v88
	v_exp_f32_e32 v89, v89
	v_exp_f32_e32 v90, v90
	v_exp_f32_e32 v91, v91
	v_mfma_f32_32x32x16_bf16 v[16:31], v[80:83], v[184:187], v[16:31]
	v_exp_f32_e32 v92, v92
	v_exp_f32_e32 v93, v93
	v_exp_f32_e32 v94, v94
	v_exp_f32_e32 v95, v95
	v_add_f32_e32 v232, v232, v88
	v_add_f32_e32 v233, v233, v89
	v_add_f32_e32 v234, v234, v90
	v_add_f32_e32 v235, v235, v91
	s_nop 0
	v_add_f32_e32 v232, v232, v92
	v_add_f32_e32 v233, v233, v93
	v_add_f32_e32 v234, v234, v94
	v_add_f32_e32 v235, v235, v95
	v_cvt_pk_bf16_f32 v88, v88, v89
	v_cvt_pk_bf16_f32 v89, v90, v91
	v_cvt_pk_bf16_f32 v90, v92, v93
	v_cvt_pk_bf16_f32 v91, v94, v95
	s_nop 1
	v_mfma_f32_32x32x16_bf16 v[0:15], v[88:91], v[188:191], v[0:15]
	v_mfma_f32_32x32x16_bf16 v[16:31], v[88:91], v[192:195], v[16:31]
	s_waitcnt vmcnt(2)
	s_waitcnt lgkmcnt(0)
	s_barrier
	s_mov_b32 s39, 0x41000000
	s_mov_b32 s25, 0
	v_add_u32_e32 v205, 0x4000, v203
	ds_read_b128 v[116:119], v205 offset:0
	ds_read_b128 v[120:123], v205 offset:512
	ds_read_b128 v[124:127], v205 offset:2048
	ds_read_b128 v[128:131], v205 offset:2560
	ds_read_b128 v[132:135], v205 offset:4096
	ds_read_b128 v[136:139], v205 offset:4608
	ds_read_b128 v[140:143], v205 offset:6144
	ds_read_b128 v[144:147], v205 offset:6656
	v_add_u32_e32 v206, 0x4000, v204
	s_waitcnt lgkmcnt(6)
	v_mfma_f32_32x32x16_bf16 v[64:79], v[116:119], v[148:151], v[100:115]
	v_mfma_f32_32x32x16_bf16 v[80:95], v[120:123], v[148:151], v[100:115]
	s_waitcnt lgkmcnt(4)
	v_mfma_f32_32x32x16_bf16 v[64:79], v[124:127], v[152:155], v[64:79]
	v_mfma_f32_32x32x16_bf16 v[80:95], v[128:131], v[152:155], v[80:95]
	s_waitcnt lgkmcnt(2)
	v_mfma_f32_32x32x16_bf16 v[64:79], v[132:135], v[156:159], v[64:79]
	v_mfma_f32_32x32x16_bf16 v[80:95], v[136:139], v[156:159], v[80:95]
	s_waitcnt lgkmcnt(0)
	v_mfma_f32_32x32x16_bf16 v[64:79], v[140:143], v[160:163], v[64:79]
	v_mfma_f32_32x32x16_bf16 v[80:95], v[144:147], v[160:163], v[80:95]
	ds_read_b64_tr_b16 v[164:165], v206 offset:0
	ds_read_b64_tr_b16 v[166:167], v206 offset:512
	ds_read_b64_tr_b16 v[168:169], v206 offset:4096
	ds_read_b64_tr_b16 v[170:171], v206 offset:4608
	ds_read_b64_tr_b16 v[172:173], v206 offset:1024
	ds_read_b64_tr_b16 v[174:175], v206 offset:1536
	ds_read_b64_tr_b16 v[176:177], v206 offset:5120
	ds_read_b64_tr_b16 v[178:179], v206 offset:5632
	ds_read_b64_tr_b16 v[180:181], v206 offset:2048
	ds_read_b64_tr_b16 v[182:183], v206 offset:2560
	ds_read_b64_tr_b16 v[184:185], v206 offset:6144
	ds_read_b64_tr_b16 v[186:187], v206 offset:6656
	ds_read_b64_tr_b16 v[188:189], v206 offset:3072
	ds_read_b64_tr_b16 v[190:191], v206 offset:3584
	ds_read_b64_tr_b16 v[192:193], v206 offset:7168
	ds_read_b64_tr_b16 v[194:195], v206 offset:7680
	s_nop 0
	s_nop 0
	v_max3_f32 v215, v64, v65, v80
	v_max3_f32 v216, v66, v67, v81
	v_max3_f32 v215, v215, v82, v83
	v_max3_f32 v216, v216, v68, v69
	v_max3_f32 v215, v215, v70, v71
	v_max3_f32 v216, v216, v84, v85
	v_max3_f32 v215, v215, v86, v87
	v_max3_f32 v216, v216, v72, v73
	v_max3_f32 v215, v215, v74, v75
	v_max3_f32 v216, v216, v88, v89
	v_max3_f32 v215, v215, v90, v91
	v_max3_f32 v216, v216, v76, v77
	v_max3_f32 v215, v215, v78, v79
	v_max3_f32 v216, v216, v92, v93
	v_max3_f32 v215, v215, v94, v95
	v_max_f32_e32 v214, v215, v216
	v_mov_b32_e32 v215, v214
	s_nop 1
	v_permlane32_swap_b32_e32 v214, v215
	s_nop 0
	v_max_f32_e32 v214, v214, v215
	v_cmp_lt_f32_e32 vcc, s39, v214
	s_cmp_lg_u64 vcc, 0
	s_cbranch_scc1 .Lxa_resc_5
.Lxa_back_6:
	v_exp_f32_e32 v64, v64
	v_exp_f32_e32 v65, v65
	v_exp_f32_e32 v66, v66
	v_exp_f32_e32 v67, v67
	v_exp_f32_e32 v68, v68
	v_exp_f32_e32 v69, v69
	v_exp_f32_e32 v70, v70
	v_exp_f32_e32 v71, v71
	s_nop 0
	v_add_f32_e32 v232, v232, v64
	v_add_f32_e32 v233, v233, v65
	v_add_f32_e32 v234, v234, v66
	v_add_f32_e32 v235, v235, v67
	v_add_f32_e32 v232, v232, v68
	v_add_f32_e32 v233, v233, v69
	v_add_f32_e32 v234, v234, v70
	v_add_f32_e32 v235, v235, v71
	v_cvt_pk_bf16_f32 v64, v64, v65
	v_cvt_pk_bf16_f32 v65, v66, v67
	v_cvt_pk_bf16_f32 v66, v68, v69
	v_cvt_pk_bf16_f32 v67, v70, v71
	s_waitcnt lgkmcnt(0)
	s_nop 0
	v_mfma_f32_32x32x16_bf16 v[0:15], v[64:67], v[164:167], v[0:15]
	v_exp_f32_e32 v72, v72
	v_exp_f32_e32 v73, v73
	v_exp_f32_e32 v74, v74
	v_exp_f32_e32 v75, v75
	v_mfma_f32_32x32x16_bf16 v[16:31], v[64:67], v[168:171], v[16:31]
	v_exp_f32_e32 v76, v76
	v_exp_f32_e32 v77, v77
	v_exp_f32_e32 v78, v78
	v_exp_f32_e32 v79, v79
	v_add_f32_e32 v232, v232, v72
	v_add_f32_e32 v233, v233, v73
	v_add_f32_e32 v234, v234, v74
	v_add_f32_e32 v235, v235, v75
	s_nop 0
	v_add_f32_e32 v232, v232, v76
	v_add_f32_e32 v233, v233, v77
	v_add_f32_e32 v234, v234, v78
	v_add_f32_e32 v235, v235, v79
	v_cvt_pk_bf16_f32 v72, v72, v73
	v_cvt_pk_bf16_f32 v73, v74, v75
	v_cvt_pk_bf16_f32 v74, v76, v77
	v_cvt_pk_bf16_f32 v75, v78, v79
	s_nop 1
	v_mfma_f32_32x32x16_bf16 v[0:15], v[72:75], v[172:175], v[0:15]
	v_exp_f32_e32 v80, v80
	v_exp_f32_e32 v81, v81
	v_exp_f32_e32 v82, v82
	v_exp_f32_e32 v83, v83
	v_mfma_f32_32x32x16_bf16 v[16:31], v[72:75], v[176:179], v[16:31]
	v_exp_f32_e32 v84, v84
	v_exp_f32_e32 v85, v85
	v_exp_f32_e32 v86, v86
	v_exp_f32_e32 v87, v87
	v_add_f32_e32 v232, v232, v80
	v_add_f32_e32 v233, v233, v81
	v_add_f32_e32 v234, v234, v82
	v_add_f32_e32 v235, v235, v83
	s_nop 0
	v_add_f32_e32 v232, v232, v84
	v_add_f32_e32 v233, v233, v85
	v_add_f32_e32 v234, v234, v86
	v_add_f32_e32 v235, v235, v87
	v_cvt_pk_bf16_f32 v80, v80, v81
	v_cvt_pk_bf16_f32 v81, v82, v83
	v_cvt_pk_bf16_f32 v82, v84, v85
	v_cvt_pk_bf16_f32 v83, v86, v87
	s_nop 1
	v_mfma_f32_32x32x16_bf16 v[0:15], v[80:83], v[180:183], v[0:15]
	v_exp_f32_e32 v88, v88
	v_exp_f32_e32 v89, v89
	v_exp_f32_e32 v90, v90
	v_exp_f32_e32 v91, v91
	v_mfma_f32_32x32x16_bf16 v[16:31], v[80:83], v[184:187], v[16:31]
	v_exp_f32_e32 v92, v92
	v_exp_f32_e32 v93, v93
	v_exp_f32_e32 v94, v94
	v_exp_f32_e32 v95, v95
	v_add_f32_e32 v232, v232, v88
	v_add_f32_e32 v233, v233, v89
	v_add_f32_e32 v234, v234, v90
	v_add_f32_e32 v235, v235, v91
	s_nop 0
	v_add_f32_e32 v232, v232, v92
	v_add_f32_e32 v233, v233, v93
	v_add_f32_e32 v234, v234, v94
	v_add_f32_e32 v235, v235, v95
	v_cvt_pk_bf16_f32 v88, v88, v89
	v_cvt_pk_bf16_f32 v89, v90, v91
	v_cvt_pk_bf16_f32 v90, v92, v93
	v_cvt_pk_bf16_f32 v91, v94, v95
	s_nop 1
	v_mfma_f32_32x32x16_bf16 v[0:15], v[88:91], v[188:191], v[0:15]
	v_mfma_f32_32x32x16_bf16 v[16:31], v[88:91], v[192:195], v[16:31]
	s_waitcnt vmcnt(0)
	s_waitcnt lgkmcnt(0)
	s_barrier
	s_mov_b32 s39, 0x41000000
	s_mov_b32 s25, 0
	v_add_u32_e32 v205, 0x6000, v203
	ds_read_b128 v[116:119], v205 offset:0
	ds_read_b128 v[120:123], v205 offset:512
	ds_read_b128 v[124:127], v205 offset:2048
	ds_read_b128 v[128:131], v205 offset:2560
	ds_read_b128 v[132:135], v205 offset:4096
	ds_read_b128 v[136:139], v205 offset:4608
	ds_read_b128 v[140:143], v205 offset:6144
	ds_read_b128 v[144:147], v205 offset:6656
	v_add_u32_e32 v206, 0x6000, v204
	s_waitcnt lgkmcnt(6)
	v_mfma_f32_32x32x16_bf16 v[64:79], v[116:119], v[148:151], v[100:115]
	v_mfma_f32_32x32x16_bf16 v[80:95], v[120:123], v[148:151], v[100:115]
	s_waitcnt lgkmcnt(4)
	v_mfma_f32_32x32x16_bf16 v[64:79], v[124:127], v[152:155], v[64:79]
	v_mfma_f32_32x32x16_bf16 v[80:95], v[128:131], v[152:155], v[80:95]
	s_waitcnt lgkmcnt(2)
	v_mfma_f32_32x32x16_bf16 v[64:79], v[132:135], v[156:159], v[64:79]
	v_mfma_f32_32x32x16_bf16 v[80:95], v[136:139], v[156:159], v[80:95]
	s_waitcnt lgkmcnt(0)
	v_mfma_f32_32x32x16_bf16 v[64:79], v[140:143], v[160:163], v[64:79]
	v_mfma_f32_32x32x16_bf16 v[80:95], v[144:147], v[160:163], v[80:95]
	ds_read_b64_tr_b16 v[164:165], v206 offset:0
	ds_read_b64_tr_b16 v[166:167], v206 offset:512
	ds_read_b64_tr_b16 v[168:169], v206 offset:4096
	ds_read_b64_tr_b16 v[170:171], v206 offset:4608
	ds_read_b64_tr_b16 v[172:173], v206 offset:1024
	ds_read_b64_tr_b16 v[174:175], v206 offset:1536
	ds_read_b64_tr_b16 v[176:177], v206 offset:5120
	ds_read_b64_tr_b16 v[178:179], v206 offset:5632
	ds_read_b64_tr_b16 v[180:181], v206 offset:2048
	ds_read_b64_tr_b16 v[182:183], v206 offset:2560
	ds_read_b64_tr_b16 v[184:185], v206 offset:6144
	ds_read_b64_tr_b16 v[186:187], v206 offset:6656
	ds_read_b64_tr_b16 v[188:189], v206 offset:3072
	ds_read_b64_tr_b16 v[190:191], v206 offset:3584
	ds_read_b64_tr_b16 v[192:193], v206 offset:7168
	ds_read_b64_tr_b16 v[194:195], v206 offset:7680
	s_nop 0
	s_nop 0
	v_max3_f32 v215, v64, v65, v80
	v_max3_f32 v216, v66, v67, v81
	v_max3_f32 v215, v215, v82, v83
	v_max3_f32 v216, v216, v68, v69
	v_max3_f32 v215, v215, v70, v71
	v_max3_f32 v216, v216, v84, v85
	v_max3_f32 v215, v215, v86, v87
	v_max3_f32 v216, v216, v72, v73
	v_max3_f32 v215, v215, v74, v75
	v_max3_f32 v216, v216, v88, v89
	v_max3_f32 v215, v215, v90, v91
	v_max3_f32 v216, v216, v76, v77
	v_max3_f32 v215, v215, v78, v79
	v_max3_f32 v216, v216, v92, v93
	v_max3_f32 v215, v215, v94, v95
	v_max_f32_e32 v214, v215, v216
	v_mov_b32_e32 v215, v214
	s_nop 1
	v_permlane32_swap_b32_e32 v214, v215
	s_nop 0
	v_max_f32_e32 v214, v214, v215
	v_cmp_lt_f32_e32 vcc, s39, v214
	s_cmp_lg_u64 vcc, 0
	s_cbranch_scc1 .Lxa_resc_7
.Lxa_back_8:
	v_exp_f32_e32 v64, v64
	v_exp_f32_e32 v65, v65
	v_exp_f32_e32 v66, v66
	v_exp_f32_e32 v67, v67
	v_exp_f32_e32 v68, v68
	v_exp_f32_e32 v69, v69
	v_exp_f32_e32 v70, v70
	v_exp_f32_e32 v71, v71
	s_nop 0
	v_add_f32_e32 v232, v232, v64
	v_add_f32_e32 v233, v233, v65
	v_add_f32_e32 v234, v234, v66
	v_add_f32_e32 v235, v235, v67
	v_add_f32_e32 v232, v232, v68
	v_add_f32_e32 v233, v233, v69
	v_add_f32_e32 v234, v234, v70
	v_add_f32_e32 v235, v235, v71
	v_cvt_pk_bf16_f32 v64, v64, v65
	v_cvt_pk_bf16_f32 v65, v66, v67
	v_cvt_pk_bf16_f32 v66, v68, v69
	v_cvt_pk_bf16_f32 v67, v70, v71
	s_waitcnt lgkmcnt(0)
	s_nop 0
	v_mfma_f32_32x32x16_bf16 v[0:15], v[64:67], v[164:167], v[0:15]
	v_exp_f32_e32 v72, v72
	v_exp_f32_e32 v73, v73
	v_exp_f32_e32 v74, v74
	v_exp_f32_e32 v75, v75
	v_mfma_f32_32x32x16_bf16 v[16:31], v[64:67], v[168:171], v[16:31]
	v_exp_f32_e32 v76, v76
	v_exp_f32_e32 v77, v77
	v_exp_f32_e32 v78, v78
	v_exp_f32_e32 v79, v79
	v_add_f32_e32 v232, v232, v72
	v_add_f32_e32 v233, v233, v73
	v_add_f32_e32 v234, v234, v74
	v_add_f32_e32 v235, v235, v75
	s_nop 0
	v_add_f32_e32 v232, v232, v76
	v_add_f32_e32 v233, v233, v77
	v_add_f32_e32 v234, v234, v78
	v_add_f32_e32 v235, v235, v79
	v_cvt_pk_bf16_f32 v72, v72, v73
	v_cvt_pk_bf16_f32 v73, v74, v75
	v_cvt_pk_bf16_f32 v74, v76, v77
	v_cvt_pk_bf16_f32 v75, v78, v79
	s_nop 1
	v_mfma_f32_32x32x16_bf16 v[0:15], v[72:75], v[172:175], v[0:15]
	v_exp_f32_e32 v80, v80
	v_exp_f32_e32 v81, v81
	v_exp_f32_e32 v82, v82
	v_exp_f32_e32 v83, v83
	v_mfma_f32_32x32x16_bf16 v[16:31], v[72:75], v[176:179], v[16:31]
	v_exp_f32_e32 v84, v84
	v_exp_f32_e32 v85, v85
	v_exp_f32_e32 v86, v86
	v_exp_f32_e32 v87, v87
	v_add_f32_e32 v232, v232, v80
	v_add_f32_e32 v233, v233, v81
	v_add_f32_e32 v234, v234, v82
	v_add_f32_e32 v235, v235, v83
	s_nop 0
	v_add_f32_e32 v232, v232, v84
	v_add_f32_e32 v233, v233, v85
	v_add_f32_e32 v234, v234, v86
	v_add_f32_e32 v235, v235, v87
	v_cvt_pk_bf16_f32 v80, v80, v81
	v_cvt_pk_bf16_f32 v81, v82, v83
	v_cvt_pk_bf16_f32 v82, v84, v85
	v_cvt_pk_bf16_f32 v83, v86, v87
	s_nop 1
	v_mfma_f32_32x32x16_bf16 v[0:15], v[80:83], v[180:183], v[0:15]
	v_exp_f32_e32 v88, v88
	v_exp_f32_e32 v89, v89
	v_exp_f32_e32 v90, v90
	v_exp_f32_e32 v91, v91
	v_mfma_f32_32x32x16_bf16 v[16:31], v[80:83], v[184:187], v[16:31]
	v_exp_f32_e32 v92, v92
	v_exp_f32_e32 v93, v93
	v_exp_f32_e32 v94, v94
	v_exp_f32_e32 v95, v95
	v_add_f32_e32 v232, v232, v88
	v_add_f32_e32 v233, v233, v89
	v_add_f32_e32 v234, v234, v90
	v_add_f32_e32 v235, v235, v91
	s_nop 0
	v_add_f32_e32 v232, v232, v92
	v_add_f32_e32 v233, v233, v93
	v_add_f32_e32 v234, v234, v94
	v_add_f32_e32 v235, v235, v95
	v_cvt_pk_bf16_f32 v88, v88, v89
	v_cvt_pk_bf16_f32 v89, v90, v91
	v_cvt_pk_bf16_f32 v90, v92, v93
	v_cvt_pk_bf16_f32 v91, v94, v95
	s_nop 1
	v_mfma_f32_32x32x16_bf16 v[0:15], v[88:91], v[188:191], v[0:15]
	v_mfma_f32_32x32x16_bf16 v[16:31], v[88:91], v[192:195], v[16:31]
	s_waitcnt vmcnt(0)
	s_waitcnt lgkmcnt(0)
	s_barrier
	s_mov_b32 s39, 0x41000000
	s_mov_b32 s25, 0
	v_add_f32_e32 v232, v232, v233
	v_add_f32_e32 v234, v234, v235
	v_add_f32_e32 v216, v232, v234
	v_mov_b32_e32 v215, v216
	s_nop 1
	v_permlane32_swap_b32_e32 v216, v215
	s_nop 0
	v_add_f32_e32 v216, v216, v215
	v_rcp_f32_e32 v217, v216
	s_nop 0
	ds_write_b32 v220, v217
	s_waitcnt lgkmcnt(0)
	ds_read_b128 v[116:119], v221 offset:0
	ds_read_b128 v[120:123], v221 offset:32
	ds_read_b128 v[124:127], v221 offset:64
	ds_read_b128 v[128:131], v221 offset:96
	v_add_u32_e32 v229, 0x2000, v224
	s_waitcnt lgkmcnt(0)
	v_mul_f32_e32 v0, v0, v116
	v_mul_f32_e32 v1, v1, v117
	v_cvt_pk_bf16_f32 v0, v0, v1
	ds_write_b16 v222, v0 offset:0
	ds_write_b16_d16_hi v222, v0 offset:64
	v_mul_f32_e32 v2, v2, v118
	v_mul_f32_e32 v3, v3, v119
	v_cvt_pk_bf16_f32 v2, v2, v3
	ds_write_b16 v222, v2 offset:128
	ds_write_b16_d16_hi v222, v2 offset:192
	v_mul_f32_e32 v4, v4, v120
	v_mul_f32_e32 v5, v5, v121
	v_cvt_pk_bf16_f32 v4, v4, v5
	ds_write_b16 v222, v4 offset:512
	ds_write_b16_d16_hi v222, v4 offset:576
	v_mul_f32_e32 v6, v6, v122
	v_mul_f32_e32 v7, v7, v123
	v_cvt_pk_bf16_f32 v6, v6, v7
	ds_write_b16 v222, v6 offset:640
	ds_write_b16_d16_hi v222, v6 offset:704
	v_mul_f32_e32 v8, v8, v124
	v_mul_f32_e32 v9, v9, v125
	v_cvt_pk_bf16_f32 v8, v8, v9
	ds_write_b16 v222, v8 offset:1024
	ds_write_b16_d16_hi v222, v8 offset:1088
	v_mul_f32_e32 v10, v10, v126
	v_mul_f32_e32 v11, v11, v127
	v_cvt_pk_bf16_f32 v10, v10, v11
	ds_write_b16 v222, v10 offset:1152
	ds_write_b16_d16_hi v222, v10 offset:1216
	v_mul_f32_e32 v12, v12, v128
	v_mul_f32_e32 v13, v13, v129
	v_cvt_pk_bf16_f32 v12, v12, v13
	ds_write_b16 v222, v12 offset:1536
	ds_write_b16_d16_hi v222, v12 offset:1600
	v_mul_f32_e32 v14, v14, v130
	v_mul_f32_e32 v15, v15, v131
	v_cvt_pk_bf16_f32 v14, v14, v15
	ds_write_b16 v222, v14 offset:1664
	ds_write_b16_d16_hi v222, v14 offset:1728
	s_waitcnt lgkmcnt(0)
	ds_read_b128 v[132:135], v223
	ds_read_b128 v[136:139], v223 offset:1024
	s_waitcnt lgkmcnt(1)
	global_store_dwordx4 v224, v[132:135], s[76:77] offset:0
	s_waitcnt lgkmcnt(0)
	global_store_dwordx4 v229, v[136:139], s[76:77] offset:0
	v_mul_f32_e32 v16, v16, v116
	v_mul_f32_e32 v17, v17, v117
	v_cvt_pk_bf16_f32 v16, v16, v17
	ds_write_b16 v222, v16 offset:0
	ds_write_b16_d16_hi v222, v16 offset:64
	v_mul_f32_e32 v18, v18, v118
	v_mul_f32_e32 v19, v19, v119
	v_cvt_pk_bf16_f32 v18, v18, v19
	ds_write_b16 v222, v18 offset:128
	ds_write_b16_d16_hi v222, v18 offset:192
	v_mul_f32_e32 v20, v20, v120
	v_mul_f32_e32 v21, v21, v121
	v_cvt_pk_bf16_f32 v20, v20, v21
	ds_write_b16 v222, v20 offset:512
	ds_write_b16_d16_hi v222, v20 offset:576
	v_mul_f32_e32 v22, v22, v122
	v_mul_f32_e32 v23, v23, v123
	v_cvt_pk_bf16_f32 v22, v22, v23
	ds_write_b16 v222, v22 offset:640
	ds_write_b16_d16_hi v222, v22 offset:704
	v_mul_f32_e32 v24, v24, v124
	v_mul_f32_e32 v25, v25, v125
	v_cvt_pk_bf16_f32 v24, v24, v25
	ds_write_b16 v222, v24 offset:1024
	ds_write_b16_d16_hi v222, v24 offset:1088
	v_mul_f32_e32 v26, v26, v126
	v_mul_f32_e32 v27, v27, v127
	v_cvt_pk_bf16_f32 v26, v26, v27
	ds_write_b16 v222, v26 offset:1152
	ds_write_b16_d16_hi v222, v26 offset:1216
	v_mul_f32_e32 v28, v28, v128
	v_mul_f32_e32 v29, v29, v129
	v_cvt_pk_bf16_f32 v28, v28, v29
	ds_write_b16 v222, v28 offset:1536
	ds_write_b16_d16_hi v222, v28 offset:1600
	v_mul_f32_e32 v30, v30, v130
	v_mul_f32_e32 v31, v31, v131
	v_cvt_pk_bf16_f32 v30, v30, v31
	ds_write_b16 v222, v30 offset:1664
	ds_write_b16_d16_hi v222, v30 offset:1728
	s_waitcnt lgkmcnt(0)
	ds_read_b128 v[132:135], v223
	ds_read_b128 v[136:139], v223 offset:1024
	s_waitcnt lgkmcnt(1)
	global_store_dwordx4 v224, v[132:135], s[76:77] offset:64
	s_waitcnt lgkmcnt(0)
	global_store_dwordx4 v229, v[136:139], s[76:77] offset:64
	s_add_i32 s26, s26, 1
	s_cmp_lt_u32 s26, 2
	s_cbranch_scc1 .Lxa_unit
	s_branch .Lxa_done
.Lxa_resc_1:
	v_max_f32_e32 v212, s25, v214
	v_add_f32_e32 v210, v210, v212
	v_exp_f32_e64 v217, -v212
	v_sub_f32_e32 v64, v64, v212
	v_sub_f32_e32 v65, v65, v212
	v_sub_f32_e32 v66, v66, v212
	v_sub_f32_e32 v67, v67, v212
	v_sub_f32_e32 v68, v68, v212
	v_sub_f32_e32 v69, v69, v212
	v_sub_f32_e32 v70, v70, v212
	v_sub_f32_e32 v71, v71, v212
	v_sub_f32_e32 v72, v72, v212
	v_sub_f32_e32 v73, v73, v212
	v_sub_f32_e32 v74, v74, v212
	v_sub_f32_e32 v75, v75, v212
	v_sub_f32_e32 v76, v76, v212
	v_sub_f32_e32 v77, v77, v212
	v_sub_f32_e32 v78, v78, v212
	v_sub_f32_e32 v79, v79, v212
	v_sub_f32_e32 v80, v80, v212
	v_sub_f32_e32 v81, v81, v212
	v_sub_f32_e32 v82, v82, v212
	v_sub_f32_e32 v83, v83, v212
	v_sub_f32_e32 v84, v84, v212
	v_sub_f32_e32 v85, v85, v212
	v_sub_f32_e32 v86, v86, v212
	v_sub_f32_e32 v87, v87, v212
	v_sub_f32_e32 v88, v88, v212
	v_sub_f32_e32 v89, v89, v212
	v_sub_f32_e32 v90, v90, v212
	v_sub_f32_e32 v91, v91, v212
	v_sub_f32_e32 v92, v92, v212
	v_sub_f32_e32 v93, v93, v212
	v_sub_f32_e32 v94, v94, v212
	v_sub_f32_e32 v95, v95, v212
	v_sub_f32_e32 v100, 0, v210
	v_sub_f32_e32 v101, 0, v210
	v_sub_f32_e32 v102, 0, v210
	v_sub_f32_e32 v103, 0, v210
	v_sub_f32_e32 v104, 0, v210
	v_sub_f32_e32 v105, 0, v210
	v_sub_f32_e32 v106, 0, v210
	v_sub_f32_e32 v107, 0, v210
	v_sub_f32_e32 v108, 0, v210
	v_sub_f32_e32 v109, 0, v210
	v_sub_f32_e32 v110, 0, v210
	v_sub_f32_e32 v111, 0, v210
	v_sub_f32_e32 v112, 0, v210
	v_sub_f32_e32 v113, 0, v210
	v_sub_f32_e32 v114, 0, v210
	v_sub_f32_e32 v115, 0, v210
	v_mul_f32_e32 v232, v232, v217
	v_mul_f32_e32 v233, v233, v217
	v_mul_f32_e32 v234, v234, v217
	v_mul_f32_e32 v235, v235, v217
	s_waitcnt lgkmcnt(0)
	ds_write_b32 v220, v217
	s_waitcnt lgkmcnt(0)
	ds_read_b128 v[116:119], v221 offset:0
	ds_read_b128 v[120:123], v221 offset:32
	ds_read_b128 v[124:127], v221 offset:64
	ds_read_b128 v[128:131], v221 offset:96
	s_waitcnt lgkmcnt(0)
	v_mul_f32_e32 v0, v0, v116
	v_mul_f32_e32 v1, v1, v117
	v_mul_f32_e32 v2, v2, v118
	v_mul_f32_e32 v3, v3, v119
	v_mul_f32_e32 v4, v4, v120
	v_mul_f32_e32 v5, v5, v121
	v_mul_f32_e32 v6, v6, v122
	v_mul_f32_e32 v7, v7, v123
	v_mul_f32_e32 v8, v8, v124
	v_mul_f32_e32 v9, v9, v125
	v_mul_f32_e32 v10, v10, v126
	v_mul_f32_e32 v11, v11, v127
	v_mul_f32_e32 v12, v12, v128
	v_mul_f32_e32 v13, v13, v129
	v_mul_f32_e32 v14, v14, v130
	v_mul_f32_e32 v15, v15, v131
	v_mul_f32_e32 v16, v16, v116
	v_mul_f32_e32 v17, v17, v117
	v_mul_f32_e32 v18, v18, v118
	v_mul_f32_e32 v19, v19, v119
	v_mul_f32_e32 v20, v20, v120
	v_mul_f32_e32 v21, v21, v121
	v_mul_f32_e32 v22, v22, v122
	v_mul_f32_e32 v23, v23, v123
	v_mul_f32_e32 v24, v24, v124
	v_mul_f32_e32 v25, v25, v125
	v_mul_f32_e32 v26, v26, v126
	v_mul_f32_e32 v27, v27, v127
	v_mul_f32_e32 v28, v28, v128
	v_mul_f32_e32 v29, v29, v129
	v_mul_f32_e32 v30, v30, v130
	v_mul_f32_e32 v31, v31, v131
	s_branch .Lxa_back_2

.Lxa_done:
	s_mov_b32 m0, s24
	s_waitcnt lgkmcnt(0)
	s_barrier
.LBB0_159:
	s_branch .LBB0_291
